# per-CU de-phasing sleep (0..31 x 64 cycles by CU index within XCD) at each step start so CUs do not issue LDS-DMA bursts in lockstep
# speedup vs baseline: 1.0149x; 1.0057x over previous
.LBB0_154:
	s_lshr_b32 s100, s74, 3
	s_and_b32 s100, s100, 31
.Ldephase_loop:
	s_cmp_eq_u32 s100, 0
	s_cbranch_scc1 .Ldephase_done
	s_sleep 1
	s_sub_u32 s100, s100, 1
	s_branch .Ldephase_loop
